# hg_seq: o-tile and state-update LDS fragment reads batched (state-update fragments read before the o-tile epilogue) instead of one LDS round trip per MFMA
# speedup vs baseline: 1.0354x; 1.0032x over previous
; #define LAS __attribute__((address_space(3)))
; __device__ __forceinline__ unsigned cvt_pk_bf16(float lo, float hi) { f32x2 f = {lo, hi}; bf16x2_t v = __builtin_convertvector(f, bf16x2_t); return __builtin_bit_cast(unsigned, v); }
; __device__ __forceinline__ void hg_seq(const Params& p, LAS unsigned char* lds, int task) {
;     ...
;         {
;             f32x4 a = {0.f, 0.f, 0.f, 0.f};
; #pragma unroll
;             for (int ks = 0; ks < 4; ++ks) {
;                 const bf16x8 sf = *(const LAS bf16x8*)(lds + ST + (vt_o * 16 + fr) * 272 + (ks * 32 + fq * 8) * 2);
;                 const bf16x8 qf = *(const LAS bf16x8*)(lds + QG + (tt * 16 + fr) * 272 + (ks * 32 + fq * 8) * 2);
;                 a = __builtin_amdgcn_mfma_f32_16x16x32_bf16(sf, qf, a, 0, 0, 0);
;             }
;             const int t = tt * 16 + fr;
;             if (t < TC) {
;                 u32x2 wv; wv.x = cvt_pk_bf16(a[0] + oi0, a[1] + oi1); wv.y = cvt_pk_bf16(a[2] + oi2, a[3] + oi3);
;                 *(u32x2*)((bf16_t*)oi + ((size_t)(h * 4 + vq) * NTOK + row0 + t) * 32 + vt_o * 16 + fq * 4) = wv;
;             }
;         }
; #pragma unroll
;         for (int vt = 0; vt < 2; ++vt) {
; #pragma unroll
;             for (int ks = 0; ks < 2; ++ks) {
;                 const bf16x8 kf = *(const LAS bf16x8*)(lds + KDT + (w * 16 + fr) * 144 + (ks * 32 + fq * 8) * 2);
;                 const bf16x8 vf = *(const LAS bf16x8*)(lds + VT + (vt * 16 + fr) * 144 + (ks * 32 + fq * 8) * 2);
;                 S[vt] = __builtin_amdgcn_mfma_f32_16x16x32_bf16(kf, vf, S[vt], 0, 0, 0);
;             }
;         }
.LBB0_622:
	ds_read_b128 v[128:131], v103 offset:40448
	ds_read_b128 v[132:135], v104
	ds_read_b128 v[136:139], v103 offset:40512
	ds_read_b128 v[140:143], v104 offset:64
	ds_read_b128 v[144:147], v103 offset:40576
	ds_read_b128 v[148:151], v104 offset:128
	ds_read_b128 v[152:155], v103 offset:40640
	ds_read_b128 v[156:159], v104 offset:192
	s_waitcnt lgkmcnt(6)
	v_mfma_f32_16x16x32_bf16 v[64:67], v[128:131], v[132:135], 0
	s_waitcnt lgkmcnt(4)
	v_mfma_f32_16x16x32_bf16 v[64:67], v[136:139], v[140:143], v[64:67]
	s_waitcnt lgkmcnt(2)
	v_mfma_f32_16x16x32_bf16 v[64:67], v[144:147], v[148:151], v[64:67]
	s_waitcnt lgkmcnt(0)
	v_mfma_f32_16x16x32_bf16 v[64:67], v[152:155], v[156:159], v[64:67]
	ds_read_b128 v[128:131], v105 offset:17408
	ds_read_b128 v[132:135], v106 offset:35840
	ds_read_b128 v[136:139], v105 offset:17472
	ds_read_b128 v[140:143], v106 offset:35904
	ds_read_b128 v[144:147], v106 offset:38144
	ds_read_b128 v[148:151], v106 offset:38208
	s_and_saveexec_b64 s[54:55], s[10:11]
	s_cbranch_execz .LBB0_624
	v_lshlrev_b32_e32 v2, 16, v88
	v_and_b32_e32 v3, 0xffff0000, v88
	v_lshlrev_b32_e32 v88, 16, v89
	v_and_b32_e32 v89, 0xffff0000, v89
	s_nop 0
	v_pk_add_f32 v[2:3], v[64:65], v[2:3]
	v_pk_add_f32 v[64:65], v[66:67], v[88:89]
	s_ashr_i32 s73, s72, 31
	v_cvt_pk_bf16_f32 v2, v2, v3
	v_cvt_pk_bf16_f32 v3, v64, v65
	v_lshl_add_u64 v[64:65], v[82:83], 0, s[72:73]
	v_lshlrev_b64 v[64:65], 6, v[64:65]
	v_lshl_add_u64 v[64:65], v[78:79], 0, v[64:65]
	global_store_dwordx2 v[64:65], v[2:3], off
.LBB0_624:
	s_or_b64 exec, exec, s[54:55]
	v_pk_mul_f32 v[6:7], v[6:7], v[62:63]
	v_pk_mul_f32 v[4:5], v[4:5], v[60:61]
	v_pk_mul_f32 v[30:31], v[30:31], v[62:63]
	v_pk_mul_f32 v[28:29], v[28:29], v[60:61]
	s_waitcnt lgkmcnt(4)
	v_mfma_f32_16x16x32_bf16 v[2:5], v[128:131], v[132:135], v[4:7]
	s_add_i32 s52, s59, 1
	s_cmp_ge_u32 s52, s86
	s_waitcnt lgkmcnt(2)
	s_nop 7
	s_nop 3
	v_mfma_f32_16x16x32_bf16 v[4:7], v[136:139], v[140:143], v[2:5]
	s_waitcnt lgkmcnt(1)
	v_mfma_f32_16x16x32_bf16 v[28:31], v[128:131], v[144:147], v[28:31]
	s_waitcnt lgkmcnt(0)
	s_barrier
	v_mfma_f32_16x16x32_bf16 v[28:31], v[136:139], v[148:151], v[28:31]
	s_cbranch_scc1 .LBB0_630
	s_waitcnt vmcnt(11)
	v_cndmask_b32_e64 v63, 0, v39, s[4:5]
	v_cndmask_b32_e64 v62, 0, v38, s[4:5]
	v_cndmask_b32_e64 v61, 0, v37, s[4:5]
	v_cndmask_b32_e64 v60, 0, v36, s[4:5]
	ds_write_b128 v101, v[60:63]
	s_and_saveexec_b64 s[54:55], s[16:17]
	v_add_u32_e32 v1, v98, v99
	s_waitcnt vmcnt(10)
	ds_write_b128 v1, v[32:35] offset:17408
	s_or_b64 exec, exec, s[54:55]
	s_waitcnt vmcnt(9)
	v_cndmask_b32_e64 v63, 0, v47, s[6:7]
	v_cndmask_b32_e64 v62, 0, v46, s[6:7]
	v_cndmask_b32_e64 v61, 0, v45, s[6:7]
	v_cndmask_b32_e64 v60, 0, v44, s[6:7]
	ds_write_b128 v101, v[60:63] offset:8704
	s_and_saveexec_b64 s[54:55], s[0:1]
	s_cbranch_execnz .LBB0_631
	s_or_b64 exec, exec, s[54:55]
	s_and_saveexec_b64 s[82:83], s[78:79]
	s_cbranch_execnz .LBB0_632

; #define LAS __attribute__((address_space(3)))
; __device__ __forceinline__ unsigned cvt_pk_bf16(float lo, float hi) { f32x2 f = {lo, hi}; bf16x2_t v = __builtin_convertvector(f, bf16x2_t); return __builtin_bit_cast(unsigned, v); }
; __device__ __forceinline__ void hg_seq(const Params& p, LAS unsigned char* lds, int task) {
;     ...
;         {
;             f32x4 a = {0.f, 0.f, 0.f, 0.f};
; #pragma unroll
;             for (int ks = 0; ks < 4; ++ks) {
;                 const bf16x8 sf = *(const LAS bf16x8*)(lds + ST + (vt_o * 16 + fr) * 272 + (ks * 32 + fq * 8) * 2);
;                 const bf16x8 qf = *(const LAS bf16x8*)(lds + QG + (tt * 16 + fr) * 272 + (ks * 32 + fq * 8) * 2);
;                 a = __builtin_amdgcn_mfma_f32_16x16x32_bf16(sf, qf, a, 0, 0, 0);
;             }
;             const int t = tt * 16 + fr;
;             if (t < TC) {
;                 u32x2 wv; wv.x = cvt_pk_bf16(a[0] + oi0, a[1] + oi1); wv.y = cvt_pk_bf16(a[2] + oi2, a[3] + oi3);
;                 *(u32x2*)((bf16_t*)oi + ((size_t)(h * 4 + vq) * NTOK + row0 + t) * 32 + vt_o * 16 + fq * 4) = wv;
;             }
;         }
; #pragma unroll
;         for (int vt = 0; vt < 2; ++vt) {
; #pragma unroll
;             for (int ks = 0; ks < 2; ++ks) {
;                 const bf16x8 kf = *(const LAS bf16x8*)(lds + KDT + (w * 16 + fr) * 144 + (ks * 32 + fq * 8) * 2);
;                 const bf16x8 vf = *(const LAS bf16x8*)(lds + VT + (vt * 16 + fr) * 144 + (ks * 32 + fq * 8) * 2);
;                 S[vt] = __builtin_amdgcn_mfma_f32_16x16x32_bf16(kf, vf, S[vt], 0, 0, 0);
;             }
;         }
.LBB0_642:
.LBB0_643:
	ds_read_b128 v[128:131], v103 offset:40448
	ds_read_b128 v[132:135], v104
	ds_read_b128 v[136:139], v103 offset:40512
	ds_read_b128 v[140:143], v104 offset:64
	ds_read_b128 v[144:147], v103 offset:40576
	ds_read_b128 v[148:151], v104 offset:128
	ds_read_b128 v[152:155], v103 offset:40640
	ds_read_b128 v[156:159], v104 offset:192
	s_waitcnt lgkmcnt(6)
	v_mfma_f32_16x16x32_bf16 v[60:63], v[128:131], v[132:135], 0
	s_waitcnt lgkmcnt(4)
	v_mfma_f32_16x16x32_bf16 v[60:63], v[136:139], v[140:143], v[60:63]
	s_waitcnt lgkmcnt(2)
	v_mfma_f32_16x16x32_bf16 v[60:63], v[144:147], v[148:151], v[60:63]
	s_waitcnt lgkmcnt(0)
	v_mfma_f32_16x16x32_bf16 v[60:63], v[152:155], v[156:159], v[60:63]
	ds_read_b128 v[128:131], v105 offset:17408
	ds_read_b128 v[132:135], v106 offset:35840
	ds_read_b128 v[136:139], v105 offset:17472
	ds_read_b128 v[140:143], v106 offset:35904
	ds_read_b128 v[144:147], v106 offset:38144
	ds_read_b128 v[148:151], v106 offset:38208
	s_and_saveexec_b64 s[54:55], s[10:11]
	s_cbranch_execz .LBB0_645
	v_lshlrev_b32_e32 v88, 16, v84
	v_and_b32_e32 v89, 0xffff0000, v84
	v_lshlrev_b32_e32 v84, 16, v85
	v_and_b32_e32 v85, 0xffff0000, v85
	s_add_i32 s62, s72, 64
	s_nop 0
	v_pk_add_f32 v[60:61], v[60:61], v[88:89]
	v_pk_add_f32 v[62:63], v[62:63], v[84:85]
	s_ashr_i32 s63, s62, 31
	v_cvt_pk_bf16_f32 v60, v60, v61
	v_cvt_pk_bf16_f32 v61, v62, v63
	v_lshl_add_u64 v[62:63], v[82:83], 0, s[62:63]
	v_lshlrev_b64 v[62:63], 6, v[62:63]
	v_lshl_add_u64 v[62:63], v[78:79], 0, v[62:63]
	global_store_dwordx2 v[62:63], v[60:61], off
.LBB0_645:
	s_or_b64 exec, exec, s[54:55]
	v_pk_mul_f32 v[6:7], v[54:55], v[6:7]
	v_pk_mul_f32 v[4:5], v[52:53], v[4:5]
	v_pk_mul_f32 v[30:31], v[54:55], v[30:31]
	v_pk_mul_f32 v[28:29], v[52:53], v[28:29]
	s_waitcnt lgkmcnt(4)
	v_mfma_f32_16x16x32_bf16 v[4:7], v[128:131], v[132:135], v[4:7]
	s_waitcnt lgkmcnt(2)
	s_nop 7
	s_nop 3
	v_mfma_f32_16x16x32_bf16 v[4:7], v[136:139], v[140:143], v[4:7]
	s_waitcnt lgkmcnt(1)
	v_mfma_f32_16x16x32_bf16 v[28:31], v[128:131], v[144:147], v[28:31]
	s_waitcnt lgkmcnt(0)
	s_barrier
	v_mfma_f32_16x16x32_bf16 v[28:31], v[136:139], v[148:151], v[28:31]
	s_andn2_b64 vcc, exec, s[80:81]
	s_addk_i32 s72, 0x80
	s_cbranch_vccz .LBB0_576
